# M3 dno units: behind the unit's load barrier each thread touches one line of the next dno unit's state/Q'/O0 image, so the next unit's load batch hits L2
# speedup vs baseline: 1.0025x; 1.0025x over previous
.LBB0_916:
	s_or_b64 exec, exec, s[20:21]
	s_ashr_i32 s19, s18, 31
	s_lshl_b64 s[2:3], s[18:19], 15
	s_add_u32 s2, s26, s2
	s_addc_u32 s3, s27, s3
	v_lshlrev_b32_e32 v1, 1, v13
	v_and_b32_e32 v2, 3, v0
	s_lshl_b32 s6, s35, 5
	v_and_b32_e32 v3, 8, v0
	v_lshrrev_b32_e32 v15, 5, v39
	v_or3_b32 v3, s6, v3, v15
	v_and_b32_e32 v15, 16, v0
	v_and_or_b32 v1, v1, 8, v2
	v_lshl_or_b32 v1, v1, 5, v15
	v_lshlrev_b32_e32 v15, 9, v3
	v_or_b32_e32 v2, v15, v1
	v_ashrrev_i32_e32 v3, 31, v2
	v_lshl_add_u64 v[18:19], s[2:3], 0, v[2:3]
	v_or_b32_e32 v17, 0x2000, v15
	global_load_dwordx4 v[42:45], v[18:19], off
	v_or_b32_e32 v18, v17, v1
	v_ashrrev_i32_e32 v19, 31, v18
	v_or_b32_e32 v22, 0x80, v1
	v_lshl_add_u64 v[18:19], s[2:3], 0, v[18:19]
	global_load_dwordx4 v[50:53], v[18:19], off
	v_or_b32_e32 v18, v17, v22
	v_ashrrev_i32_e32 v19, 31, v18
	v_lshl_add_u64 v[18:19], s[2:3], 0, v[18:19]
	v_ashrrev_i32_e32 v3, 31, v15
	global_load_dwordx4 v[54:57], v[18:19], off
	v_or_b32_e32 v18, v15, v22
	s_nop 0
	v_lshl_add_u64 v[2:3], s[2:3], 0, v[2:3]
	v_ashrrev_i32_e32 v19, 31, v18
	v_or_b32_e32 v114, 0x2400, v15
	global_load_dwordx4 v[46:49], v[2:3], off offset:128
	global_load_dwordx4 v[58:61], v[2:3], off offset:1024
	v_lshl_add_u64 v[20:21], s[2:3], 0, v[18:19]
	v_or_b32_e32 v18, v114, v1
	v_ashrrev_i32_e32 v19, 31, v18
	v_lshl_add_u64 v[18:19], s[2:3], 0, v[18:19]
	global_load_dwordx4 v[62:65], v[2:3], off offset:3072
	global_load_dwordx4 v[66:69], v[20:21], off offset:1024
	global_load_dwordx4 v[70:73], v[18:19], off
	global_load_dwordx4 v[78:81], v[2:3], off offset:2048
	v_or_b32_e32 v18, v114, v22
	v_ashrrev_i32_e32 v19, 31, v18
	v_lshl_add_u64 v[18:19], s[2:3], 0, v[18:19]
	global_load_dwordx4 v[74:77], v[18:19], off
	global_load_dwordx4 v[94:97], v[20:21], off offset:3072
	v_or_b32_e32 v115, 0x2800, v15
	v_or_b32_e32 v2, v115, v1
	global_load_dwordx4 v[82:85], v[20:21], off offset:2048
	v_ashrrev_i32_e32 v3, 31, v2
	v_lshl_add_u64 v[2:3], s[2:3], 0, v[2:3]
	global_load_dwordx4 v[86:89], v[2:3], off
	v_or_b32_e32 v2, v115, v22
	v_or_b32_e32 v115, 0x2c00, v15
	v_or_b32_e32 v20, v115, v1
	v_ashrrev_i32_e32 v3, 31, v2
	v_ashrrev_i32_e32 v21, 31, v20
	v_lshl_add_u64 v[2:3], s[2:3], 0, v[2:3]
	v_lshl_add_u64 v[20:21], s[2:3], 0, v[20:21]
	global_load_dwordx4 v[90:93], v[2:3], off
	global_load_dwordx4 v[98:101], v[20:21], off
	v_or_b32_e32 v20, v115, v22
	v_ashrrev_i32_e32 v21, 31, v20
	v_lshl_add_u64 v[20:21], s[2:3], 0, v[20:21]
	global_load_dwordx4 v[102:105], v[20:21], off
	v_mad_i64_i32 v[2:3], s[18:19], v28, s28, v[26:27]
	s_lshl_b32 s6, s34, 8
	s_lshl_b32 s18, s35, 6
	v_lshrrev_b32_e32 v0, 1, v0
	v_lshl_add_u64 v[2:3], v[2:3], 0, s[6:7]
	s_ashr_i32 s19, s18, 31
	v_and_b32_e32 v41, 24, v0
	v_lshl_add_u64 v[2:3], s[18:19], 1, v[2:3]
	v_lshlrev_b32_e32 v24, 1, v41
	v_lshl_add_u64 v[0:1], v[2:3], 0, v[24:25]
	v_add_co_u32_e64 v108, s[2:3], s29, v0
	v_lshl_add_u64 v[106:107], v[0:1], 0, s[16:17]
	s_nop 0
	v_addc_co_u32_e64 v109, s[2:3], 0, v1, s[2:3]
	v_or_b32_e32 v140, s18, v41
	v_lshlrev_b32_e32 v140, 2, v140
	global_load_dwordx4 v[124:127], v140, s[38:39] offset:0
	global_load_dwordx4 v[128:131], v140, s[38:39] offset:16
	global_load_dwordx4 v[132:135], v140, s[38:39] offset:128
	global_load_dwordx4 v[136:139], v140, s[38:39] offset:144
	global_load_dwordx4 v[20:23], v[108:109], off offset:3072
	global_load_dwordx4 v[0:3], v[106:107], off offset:64
	v_lshlrev_b32_e32 v115, 4, v13
	v_and_b32_e32 v13, 0x70, v115
	v_add_u32_e32 v24, v31, v14
	s_waitcnt vmcnt(0) lgkmcnt(0)
	s_barrier
	v_readlane_b32 s44, v254, 0
	s_add_i32 s42, s33, s22
	s_cmpk_lt_i32 s42, 0x400
	s_cselect_b32 s42, s42, s33
	s_lshr_b32 s43, s42, 9
	s_and_b32 s42, s42, 0x1ff
	s_mul_i32 s43, s43, 0x204
	s_add_i32 s42, s42, s43
	s_add_i32 s42, s42, 4
	s_mul_i32 s43, s42, 0x8000
	s_mul_i32 s42, s42, 0x18000
	s_add_i32 s42, s42, 0x8000
	s_andn2_b32 s44, s44, 63
	s_cmp_lt_u32 s44, 0x100
	s_cselect_b32 s42, s43, s42
	s_cselect_b32 s46, s26, s24
	s_cselect_b32 s47, s27, s25
	v_lshl_add_u32 v141, v30, 7, s42
	global_load_dword v141, v141, s[46:47]
	s_nop 0
	s_nop 0
	s_nop 0
	s_nop 0
	s_nop 0
	s_nop 0
	s_nop 0
	s_nop 0
	v_lshlrev_b32_e32 v16, 16, v8
	v_and_b32_e32 v17, 0xffff0000, v8
	v_lshlrev_b32_e32 v18, 16, v9
	v_and_b32_e32 v19, 0xffff0000, v9
	v_lshlrev_b32_e32 v8, 16, v10
	v_and_b32_e32 v9, 0xffff0000, v10
	v_xad_u32 v10, v13, v12, v24
	ds_read_b128 v[106:109], v10 offset:32768
	v_or_b32_e32 v14, 64, v12
	v_xad_u32 v14, v13, v14, v24
	ds_read_b128 v[110:113], v14 offset:32768
	s_waitcnt lgkmcnt(0)
	v_mfma_f32_16x16x32_bf16 v[14:17], v[42:45], v[106:109], v[16:19]
	v_lshlrev_b32_e32 v10, 16, v11
	v_and_b32_e32 v11, 0xffff0000, v11
	s_nop 0
	v_or_b32_e32 v18, 0x80, v12
	v_xad_u32 v18, v13, v18, v24
	s_waitcnt vmcnt(14)
	v_mfma_f32_16x16x32_bf16 v[8:11], v[46:49], v[106:109], v[8:11]
	v_lshlrev_b32_e32 v42, 16, v4
	v_and_b32_e32 v43, 0xffff0000, v4
	v_lshlrev_b32_e32 v44, 16, v5
	v_and_b32_e32 v45, 0xffff0000, v5
	ds_read_b128 v[46:49], v18 offset:32768
	s_waitcnt vmcnt(13)
	v_mfma_f32_16x16x32_bf16 v[14:17], v[58:61], v[110:113], v[14:17]
	v_or_b32_e32 v12, 0xc0, v12
	v_xad_u32 v12, v13, v12, v24
	v_lshlrev_b32_e32 v4, 16, v6
	v_mfma_f32_16x16x32_bf16 v[42:45], v[50:53], v[106:109], v[42:45]
	v_and_b32_e32 v5, 0xffff0000, v6
	v_lshlrev_b32_e32 v6, 16, v7
	v_and_b32_e32 v7, 0xffff0000, v7
	s_waitcnt vmcnt(11)
	v_mfma_f32_16x16x32_bf16 v[8:11], v[66:69], v[110:113], v[8:11]
	ds_read_b128 v[50:53], v12 offset:32768
	v_cmp_gt_u32_e64 s[2:3], 16, v39
	v_mfma_f32_16x16x32_bf16 v[4:7], v[54:57], v[106:109], v[4:7]
	s_waitcnt vmcnt(10)
	v_mfma_f32_16x16x32_bf16 v[42:45], v[70:73], v[110:113], v[42:45]
	s_waitcnt vmcnt(9) lgkmcnt(1)
	v_mfma_f32_16x16x32_bf16 v[12:15], v[78:81], v[46:49], v[14:17]
	s_waitcnt vmcnt(6)
	v_mfma_f32_16x16x32_bf16 v[8:11], v[82:85], v[46:49], v[8:11]
	v_mfma_f32_16x16x32_bf16 v[4:7], v[74:77], v[110:113], v[4:7]
	s_waitcnt vmcnt(5)
	v_mfma_f32_16x16x32_bf16 v[42:45], v[86:89], v[46:49], v[42:45]
	s_waitcnt lgkmcnt(0)
	v_mfma_f32_16x16x32_bf16 v[16:19], v[62:65], v[50:53], v[12:15]
	v_mfma_f32_16x16x32_bf16 v[12:15], v[94:97], v[50:53], v[8:11]
	s_waitcnt vmcnt(4)
	v_mfma_f32_16x16x32_bf16 v[4:7], v[90:93], v[46:49], v[4:7]
	s_nop 4
	v_mul_f32_e32 v24, v17, v17
	v_fmac_f32_e32 v24, v16, v16
	s_waitcnt vmcnt(3)
	v_mfma_f32_16x16x32_bf16 v[8:11], v[98:101], v[50:53], v[42:45]
	s_nop 2
	v_mul_f32_e32 v42, v19, v19
	v_fmac_f32_e32 v42, v18, v18
	v_add_f32_e32 v24, v24, v42
	v_mul_f32_e32 v42, v13, v13
	v_mul_f32_e32 v43, v15, v15
	v_fmac_f32_e32 v42, v12, v12
	v_fmac_f32_e32 v43, v14, v14
	s_waitcnt vmcnt(2)
	v_mfma_f32_16x16x32_bf16 v[4:7], v[102:105], v[50:53], v[4:7]
	v_add_f32_e32 v42, v42, v43
	v_add_f32_e32 v24, v24, v42
	v_mul_f32_e32 v42, v9, v9
	v_mul_f32_e32 v43, v11, v11
	v_fmac_f32_e32 v42, v8, v8
	v_fmac_f32_e32 v43, v10, v10
	v_add_f32_e32 v42, v42, v43
	v_add_f32_e32 v24, v24, v42
	v_mul_f32_e32 v42, v5, v5
	v_mul_f32_e32 v43, v7, v7
	v_fmac_f32_e32 v42, v4, v4
	v_fmac_f32_e32 v43, v6, v6
	v_add_f32_e32 v42, v42, v43
	v_add_f32_e32 v24, v24, v42
	ds_bpermute_b32 v42, v36, v24
	s_waitcnt lgkmcnt(0)
	v_add_f32_e32 v42, v24, v42
	ds_bpermute_b32 v43, v37, v42
	v_lshlrev_b32_e32 v24, 3, v40
	s_and_saveexec_b64 s[20:21], s[2:3]
	s_cbranch_execz .LBB0_918
	s_lshl_b32 s2, s35, 2
	v_add3_u32 v39, v31, v24, s2
	s_waitcnt lgkmcnt(0)
	v_add_f32_e32 v40, v42, v43
	ds_write_b32 v39, v40 offset:49152

.LBB0_2425:
	s_or_b64 exec, exec, s[20:21]
	s_ashr_i32 s19, s18, 31
	s_lshl_b64 s[2:3], s[18:19], 15
	s_add_u32 s2, s26, s2
	s_addc_u32 s3, s27, s3
	v_lshlrev_b32_e32 v1, 1, v13
	v_and_b32_e32 v2, 3, v0
	s_lshl_b32 s6, s35, 5
	v_and_b32_e32 v3, 8, v0
	v_lshrrev_b32_e32 v15, 5, v39
	v_or3_b32 v3, s6, v3, v15
	v_and_b32_e32 v15, 16, v0
	v_and_or_b32 v1, v1, 8, v2
	v_lshl_or_b32 v1, v1, 5, v15
	v_lshlrev_b32_e32 v15, 9, v3
	v_or_b32_e32 v2, v15, v1
	v_ashrrev_i32_e32 v3, 31, v2
	v_lshl_add_u64 v[18:19], s[2:3], 0, v[2:3]
	v_or_b32_e32 v17, 0x2000, v15
	global_load_dwordx4 v[42:45], v[18:19], off
	v_or_b32_e32 v18, v17, v1
	v_ashrrev_i32_e32 v19, 31, v18
	v_or_b32_e32 v22, 0x80, v1
	v_lshl_add_u64 v[18:19], s[2:3], 0, v[18:19]
	global_load_dwordx4 v[50:53], v[18:19], off
	v_or_b32_e32 v18, v17, v22
	v_ashrrev_i32_e32 v19, 31, v18
	v_lshl_add_u64 v[18:19], s[2:3], 0, v[18:19]
	v_ashrrev_i32_e32 v3, 31, v15
	global_load_dwordx4 v[54:57], v[18:19], off
	v_or_b32_e32 v18, v15, v22
	s_nop 0
	v_lshl_add_u64 v[2:3], s[2:3], 0, v[2:3]
	v_ashrrev_i32_e32 v19, 31, v18
	v_or_b32_e32 v114, 0x2400, v15
	global_load_dwordx4 v[46:49], v[2:3], off offset:128
	global_load_dwordx4 v[58:61], v[2:3], off offset:1024
	v_lshl_add_u64 v[20:21], s[2:3], 0, v[18:19]
	v_or_b32_e32 v18, v114, v1
	v_ashrrev_i32_e32 v19, 31, v18
	v_lshl_add_u64 v[18:19], s[2:3], 0, v[18:19]
	global_load_dwordx4 v[62:65], v[2:3], off offset:3072
	global_load_dwordx4 v[66:69], v[20:21], off offset:1024
	global_load_dwordx4 v[70:73], v[18:19], off
	global_load_dwordx4 v[78:81], v[2:3], off offset:2048
	v_or_b32_e32 v18, v114, v22
	v_ashrrev_i32_e32 v19, 31, v18
	v_lshl_add_u64 v[18:19], s[2:3], 0, v[18:19]
	global_load_dwordx4 v[74:77], v[18:19], off
	global_load_dwordx4 v[94:97], v[20:21], off offset:3072
	v_or_b32_e32 v115, 0x2800, v15
	v_or_b32_e32 v2, v115, v1
	global_load_dwordx4 v[82:85], v[20:21], off offset:2048
	v_ashrrev_i32_e32 v3, 31, v2
	v_lshl_add_u64 v[2:3], s[2:3], 0, v[2:3]
	global_load_dwordx4 v[86:89], v[2:3], off
	v_or_b32_e32 v2, v115, v22
	v_or_b32_e32 v115, 0x2c00, v15
	v_or_b32_e32 v20, v115, v1
	v_ashrrev_i32_e32 v3, 31, v2
	v_ashrrev_i32_e32 v21, 31, v20
	v_lshl_add_u64 v[2:3], s[2:3], 0, v[2:3]
	v_lshl_add_u64 v[20:21], s[2:3], 0, v[20:21]
	global_load_dwordx4 v[90:93], v[2:3], off
	global_load_dwordx4 v[98:101], v[20:21], off
	v_or_b32_e32 v20, v115, v22
	v_ashrrev_i32_e32 v21, 31, v20
	v_lshl_add_u64 v[20:21], s[2:3], 0, v[20:21]
	global_load_dwordx4 v[102:105], v[20:21], off
	v_mad_i64_i32 v[2:3], s[18:19], v28, s28, v[26:27]
	s_lshl_b32 s6, s34, 8
	s_lshl_b32 s18, s35, 6
	v_lshrrev_b32_e32 v0, 1, v0
	v_lshl_add_u64 v[2:3], v[2:3], 0, s[6:7]
	s_ashr_i32 s19, s18, 31
	v_and_b32_e32 v41, 24, v0
	v_lshl_add_u64 v[2:3], s[18:19], 1, v[2:3]
	v_lshlrev_b32_e32 v24, 1, v41
	v_lshl_add_u64 v[0:1], v[2:3], 0, v[24:25]
	v_add_co_u32_e64 v108, s[2:3], s29, v0
	v_lshl_add_u64 v[106:107], v[0:1], 0, s[16:17]
	s_nop 0
	v_addc_co_u32_e64 v109, s[2:3], 0, v1, s[2:3]
	v_or_b32_e32 v140, s18, v41
	v_lshlrev_b32_e32 v140, 2, v140
	global_load_dwordx4 v[124:127], v140, s[38:39] offset:512
	global_load_dwordx4 v[128:131], v140, s[38:39] offset:528
	global_load_dwordx4 v[132:135], v140, s[38:39] offset:640
	global_load_dwordx4 v[136:139], v140, s[38:39] offset:656
	global_load_dwordx4 v[20:23], v[108:109], off offset:3072
	global_load_dwordx4 v[0:3], v[106:107], off offset:64
	v_lshlrev_b32_e32 v115, 4, v13
	v_and_b32_e32 v13, 0x70, v115
	v_add_u32_e32 v24, v31, v14
	s_waitcnt vmcnt(0) lgkmcnt(0)
	s_barrier
	v_readlane_b32 s44, v254, 0
	s_add_i32 s42, s33, s22
	s_cmpk_lt_i32 s42, 0x400
	s_cselect_b32 s42, s42, s33
	s_lshr_b32 s43, s42, 9
	s_and_b32 s42, s42, 0x1ff
	s_mul_i32 s43, s43, 0x204
	s_add_i32 s42, s42, s43
	s_add_i32 s42, s42, 4
	s_mul_i32 s43, s42, 0x8000
	s_mul_i32 s42, s42, 0x18000
	s_add_i32 s42, s42, 0x8000
	s_andn2_b32 s44, s44, 63
	s_cmp_lt_u32 s44, 0x100
	s_cselect_b32 s42, s43, s42
	s_cselect_b32 s46, s26, s24
	s_cselect_b32 s47, s27, s25
	v_lshl_add_u32 v141, v30, 7, s42
	global_load_dword v141, v141, s[46:47]
	s_nop 0
	s_nop 0
	s_nop 0
	s_nop 0
	s_nop 0
	s_nop 0
	s_nop 0
	s_nop 0
	v_lshlrev_b32_e32 v16, 16, v8
	v_and_b32_e32 v17, 0xffff0000, v8
	v_lshlrev_b32_e32 v18, 16, v9
	v_and_b32_e32 v19, 0xffff0000, v9
	v_lshlrev_b32_e32 v8, 16, v10
	v_and_b32_e32 v9, 0xffff0000, v10
	v_xad_u32 v10, v13, v12, v24
	ds_read_b128 v[106:109], v10 offset:32768
	v_or_b32_e32 v14, 64, v12
	v_xad_u32 v14, v13, v14, v24
	ds_read_b128 v[110:113], v14 offset:32768
	s_waitcnt lgkmcnt(0)
	v_mfma_f32_16x16x32_bf16 v[14:17], v[42:45], v[106:109], v[16:19]
	v_lshlrev_b32_e32 v10, 16, v11
	v_and_b32_e32 v11, 0xffff0000, v11
	s_nop 0
	v_or_b32_e32 v18, 0x80, v12
	v_xad_u32 v18, v13, v18, v24
	s_waitcnt vmcnt(14)
	v_mfma_f32_16x16x32_bf16 v[8:11], v[46:49], v[106:109], v[8:11]
	v_lshlrev_b32_e32 v42, 16, v4
	v_and_b32_e32 v43, 0xffff0000, v4
	v_lshlrev_b32_e32 v44, 16, v5
	v_and_b32_e32 v45, 0xffff0000, v5
	ds_read_b128 v[46:49], v18 offset:32768
	s_waitcnt vmcnt(13)
	v_mfma_f32_16x16x32_bf16 v[14:17], v[58:61], v[110:113], v[14:17]
	v_or_b32_e32 v12, 0xc0, v12
	v_xad_u32 v12, v13, v12, v24
	v_lshlrev_b32_e32 v4, 16, v6
	v_mfma_f32_16x16x32_bf16 v[42:45], v[50:53], v[106:109], v[42:45]
	v_and_b32_e32 v5, 0xffff0000, v6
	v_lshlrev_b32_e32 v6, 16, v7
	v_and_b32_e32 v7, 0xffff0000, v7
	s_waitcnt vmcnt(11)
	v_mfma_f32_16x16x32_bf16 v[8:11], v[66:69], v[110:113], v[8:11]
	ds_read_b128 v[50:53], v12 offset:32768
	v_cmp_gt_u32_e64 s[2:3], 16, v39
	v_mfma_f32_16x16x32_bf16 v[4:7], v[54:57], v[106:109], v[4:7]
	s_waitcnt vmcnt(10)
	v_mfma_f32_16x16x32_bf16 v[42:45], v[70:73], v[110:113], v[42:45]
	s_waitcnt vmcnt(9) lgkmcnt(1)
	v_mfma_f32_16x16x32_bf16 v[12:15], v[78:81], v[46:49], v[14:17]
	s_waitcnt vmcnt(6)
	v_mfma_f32_16x16x32_bf16 v[8:11], v[82:85], v[46:49], v[8:11]
	v_mfma_f32_16x16x32_bf16 v[4:7], v[74:77], v[110:113], v[4:7]
	s_waitcnt vmcnt(5)
	v_mfma_f32_16x16x32_bf16 v[42:45], v[86:89], v[46:49], v[42:45]
	s_waitcnt lgkmcnt(0)
	v_mfma_f32_16x16x32_bf16 v[16:19], v[62:65], v[50:53], v[12:15]
	v_mfma_f32_16x16x32_bf16 v[12:15], v[94:97], v[50:53], v[8:11]
	s_waitcnt vmcnt(4)
	v_mfma_f32_16x16x32_bf16 v[4:7], v[90:93], v[46:49], v[4:7]
	s_nop 4
	v_mul_f32_e32 v24, v17, v17
	v_fmac_f32_e32 v24, v16, v16
	s_waitcnt vmcnt(3)
	v_mfma_f32_16x16x32_bf16 v[8:11], v[98:101], v[50:53], v[42:45]
	s_nop 2
	v_mul_f32_e32 v42, v19, v19
	v_fmac_f32_e32 v42, v18, v18
	v_add_f32_e32 v24, v24, v42
	v_mul_f32_e32 v42, v13, v13
	v_mul_f32_e32 v43, v15, v15
	v_fmac_f32_e32 v42, v12, v12
	v_fmac_f32_e32 v43, v14, v14
	s_waitcnt vmcnt(2)
	v_mfma_f32_16x16x32_bf16 v[4:7], v[102:105], v[50:53], v[4:7]
	v_add_f32_e32 v42, v42, v43
	v_add_f32_e32 v24, v24, v42
	v_mul_f32_e32 v42, v9, v9
	v_mul_f32_e32 v43, v11, v11
	v_fmac_f32_e32 v42, v8, v8
	v_fmac_f32_e32 v43, v10, v10
	v_add_f32_e32 v42, v42, v43
	v_add_f32_e32 v24, v24, v42
	v_mul_f32_e32 v42, v5, v5
	v_mul_f32_e32 v43, v7, v7
	v_fmac_f32_e32 v42, v4, v4
	v_fmac_f32_e32 v43, v6, v6
	v_add_f32_e32 v42, v42, v43
	v_add_f32_e32 v24, v24, v42
	ds_bpermute_b32 v42, v36, v24
	s_waitcnt lgkmcnt(0)
	v_add_f32_e32 v42, v24, v42
	ds_bpermute_b32 v43, v37, v42
	v_lshlrev_b32_e32 v24, 3, v40
	s_and_saveexec_b64 s[20:21], s[2:3]
	s_cbranch_execz .LBB0_2427
	s_lshl_b32 s2, s35, 2
	v_add3_u32 v39, v31, v24, s2
	s_waitcnt lgkmcnt(0)
	v_add_f32_e32 v40, v42, v43
	ds_write_b32 v39, v40 offset:49152
